# grid syncs 2-8 arrive/poll on a device-memory counter word instead of the runtime sync struct
# speedup vs baseline: 1.0247x; 1.0247x over previous
; __global__ void __launch_bounds__(512, 2) hymba_fwd(Params p0) {
;     ...
;         if (phx + 1 < p0.ph_hi + (DUP_PHASE >= 0 ? 1 : 0)) grid.sync();
.LBB0_952:
	v_readlane_b32 s2, v254, 3
	v_readlane_b32 s3, v254, 4
	buffer_wbl2 sc1
	s_load_dwordx2 s[8:9], s[2:3], 0x58
	v_readlane_b32 s4, v254, 28
	v_readlane_b32 s5, v254, 29
	v_readlane_b32 s6, v254, 1
	s_add_u32 s2, s4, 0x229f1fe0
	s_addc_u32 s3, s5, 0
	s_cmp_lg_u32 s6, 1
	s_cbranch_scc1 .Lgsync_own_word
	global_atomic_and v149, v149, s[2:3] offset:32
	s_waitcnt lgkmcnt(0)
	s_mov_b64 s[2:3], s[8:9]
.Lgsync_own_word:
	s_waitcnt vmcnt(0) lgkmcnt(0)
	s_mov_b64 s[4:5], exec
	v_mbcnt_lo_u32_b32 v5, s4, 0
	v_mbcnt_hi_u32_b32 v5, s5, v5
	v_cmp_eq_u32_e32 vcc, 0, v5
	global_load_dword v4, v149, s[8:9] offset:40
	s_and_saveexec_b64 s[6:7], vcc
	s_cbranch_execz .LBB0_954
	s_bcnt1_i32_b64 s4, s[4:5]
	v_mov_b32_e32 v6, s4
	global_atomic_add v6, v149, v6, s[2:3] offset:32 sc0

; __global__ void __launch_bounds__(512, 2) hymba_fwd(Params p0) {
;     ...
;         if (phx + 1 < p0.ph_hi + (DUP_PHASE >= 0 ? 1 : 0)) grid.sync();
.LBB0_958:
	s_mov_b64 s[4:5], 0
	s_mov_b32 s6, 0
.LBB0_959:
	s_sleep 1
	global_load_dword v5, v149, s[2:3] offset:32 sc1
	s_add_u32 s6, s6, 1
	s_cmp_ge_u32 s6, 0x20000
	s_cbranch_scc1 .Lgsync_spin_cap
	s_waitcnt vmcnt(0)
	v_and_b32_e32 v5, 0xffff0000, v5
	v_cmp_ne_u32_e32 vcc, v5, v4
	s_or_b64 s[4:5], vcc, s[4:5]
	s_andn2_b64 exec, exec, s[4:5]
	s_cbranch_execnz .LBB0_959
.Lgsync_spin_cap:
	s_getpc_b64 s[98:99]
